# prologue adaLN GEMV inner loop by hand: 64 rows of ada_w in flight, scalars read one 4-row group ahead, products packed over row pairs
# speedup vs baseline: 1.0102x; 1.0086x over previous
; #define LAS __attribute__((address_space(3)))
; __device__ __forceinline__ void prologue(const __attribute__((address_space(4))) Args& a, ldsp lds, int gw, int NGW, int wave, int lane, const int tid, const int bid, const int G) {
;     ...
;     for (int u = bid; u < 4 * 96; u += G) {
;         const int layer = u / 96, col0 = (u % 96) * 64;
;         const float* Wl = a.ada_w + (size_t)layer * D * NMOD + col0 + lane;
;         float acc[9];
; #pragma unroll
;         for (int j = 0; j < 9; ++j) acc[j] = 0.f;
;         for (int k = wave * 128; k < wave * 128 + 128; k += 16) {
;             float wv[16];
; #pragma unroll
;             for (int q = 0; q < 16; ++q) wv[q] = Wl[(size_t)(k + q) * NMOD];
; #pragma unroll
;             for (int q4 = 0; q4 < 4; ++q4)
; #pragma unroll
;                 for (int j = 0; j < 9; ++j) { const f32x4 s4 = *(const LAS f32x4*)(sc + j * D + k + 4 * q4); acc[j] += s4[0] * wv[4 * q4] + s4[1] * wv[4 * q4 + 1] + s4[2] * wv[4 * q4 + 2] + s4[3] * wv[4 * q4 + 3]; }
.LBB0_1277:
	s_mul_hi_i32 s6, s96, 0x2aaaaaab
	s_lshr_b32 s7, s6, 31
	s_ashr_i32 s6, s6, 4
	s_add_i32 s12, s6, s7
	s_mul_i32 s6, s12, 0x60
	s_sub_i32 s6, s96, s6
	s_lshl_b32 s6, s6, 6
	s_ashr_i32 s7, s6, 31
	s_mul_i32 s14, s12, 0x1800000
	s_lshl_b64 s[8:9], s[6:7], 2
	s_mul_hi_i32 s13, s12, 0x1800000
	s_add_u32 s8, s14, s8
	s_addc_u32 s9, s13, s9
	v_mov_b32_e32 v78, 0
	v_lshl_add_u64 v[76:77], v[74:75], 0, s[8:9]
	s_mov_b32 s8, s3
	s_mov_b32 s9, s1
	v_mov_b32_e32 v79, v78
	v_mov_b32_e32 v84, v78
	v_mov_b32_e32 v85, v78
	v_mov_b32_e32 v82, v78
	v_mov_b32_e32 v83, v78
	v_mov_b32_e32 v80, v78
	v_mov_b32_e32 v81, v78
	v_mov_b32_e32 v92, v78
	v_readfirstlane_b32 s22, v76
	v_readfirstlane_b32 s23, v77
	v_lshlrev_b32_e32 v0, 2, v87
	v_mov_b32_e32 v1, s8
	s_sub_u32 s22, s22, 0x5a000
	s_subb_u32 s23, s23, 0
	global_load_dword v2, v0, s[22:23]
	s_add_u32 s22, s22, 0x6000
	s_addc_u32 s23, s23, 0
	global_load_dword v3, v0, s[22:23]
	s_add_u32 s22, s22, 0x6000
	s_addc_u32 s23, s23, 0
	global_load_dword v4, v0, s[22:23]
	s_add_u32 s22, s22, 0x6000
	s_addc_u32 s23, s23, 0
	global_load_dword v5, v0, s[22:23]
	s_add_u32 s22, s22, 0x6000
	s_addc_u32 s23, s23, 0
	global_load_dword v6, v0, s[22:23]
	s_add_u32 s22, s22, 0x6000
	s_addc_u32 s23, s23, 0
	global_load_dword v7, v0, s[22:23]
	s_add_u32 s22, s22, 0x6000
	s_addc_u32 s23, s23, 0
	global_load_dword v8, v0, s[22:23]
	s_add_u32 s22, s22, 0x6000
	s_addc_u32 s23, s23, 0
	global_load_dword v9, v0, s[22:23]
	s_add_u32 s22, s22, 0x6000
	s_addc_u32 s23, s23, 0
	global_load_dword v10, v0, s[22:23]
	s_add_u32 s22, s22, 0x6000
	s_addc_u32 s23, s23, 0
	global_load_dword v11, v0, s[22:23]
	s_add_u32 s22, s22, 0x6000
	s_addc_u32 s23, s23, 0
	global_load_dword v12, v0, s[22:23]
	s_add_u32 s22, s22, 0x6000
	s_addc_u32 s23, s23, 0
	global_load_dword v13, v0, s[22:23]
	s_add_u32 s22, s22, 0x6000
	s_addc_u32 s23, s23, 0
	global_load_dword v14, v0, s[22:23]
	s_add_u32 s22, s22, 0x6000
	s_addc_u32 s23, s23, 0
	global_load_dword v15, v0, s[22:23]
	s_add_u32 s22, s22, 0x6000
	s_addc_u32 s23, s23, 0
	global_load_dword v16, v0, s[22:23]
	s_add_u32 s22, s22, 0x6000
	s_addc_u32 s23, s23, 0
	global_load_dword v17, v0, s[22:23]
	s_add_u32 s22, s22, 0x6000
	s_addc_u32 s23, s23, 0
	global_load_dword v18, v0, s[22:23]
	s_add_u32 s22, s22, 0x6000
	s_addc_u32 s23, s23, 0
	global_load_dword v19, v0, s[22:23]
	s_add_u32 s22, s22, 0x6000
	s_addc_u32 s23, s23, 0
	global_load_dword v20, v0, s[22:23]
	s_add_u32 s22, s22, 0x6000
	s_addc_u32 s23, s23, 0
	global_load_dword v21, v0, s[22:23]
	s_add_u32 s22, s22, 0x6000
	s_addc_u32 s23, s23, 0
	global_load_dword v22, v0, s[22:23]
	s_add_u32 s22, s22, 0x6000
	s_addc_u32 s23, s23, 0
	global_load_dword v23, v0, s[22:23]
	s_add_u32 s22, s22, 0x6000
	s_addc_u32 s23, s23, 0
	global_load_dword v24, v0, s[22:23]
	s_add_u32 s22, s22, 0x6000
	s_addc_u32 s23, s23, 0
	global_load_dword v25, v0, s[22:23]
	s_add_u32 s22, s22, 0x6000
	s_addc_u32 s23, s23, 0
	global_load_dword v26, v0, s[22:23]
	s_add_u32 s22, s22, 0x6000
	s_addc_u32 s23, s23, 0
	global_load_dword v27, v0, s[22:23]
	s_add_u32 s22, s22, 0x6000
	s_addc_u32 s23, s23, 0
	global_load_dword v28, v0, s[22:23]
	s_add_u32 s22, s22, 0x6000
	s_addc_u32 s23, s23, 0
	global_load_dword v29, v0, s[22:23]
	s_add_u32 s22, s22, 0x6000
	s_addc_u32 s23, s23, 0
	global_load_dword v30, v0, s[22:23]
	s_add_u32 s22, s22, 0x6000
	s_addc_u32 s23, s23, 0
	global_load_dword v31, v0, s[22:23]
	s_add_u32 s22, s22, 0x6000
	s_addc_u32 s23, s23, 0
	global_load_dword v32, v0, s[22:23]
	s_add_u32 s22, s22, 0x6000
	s_addc_u32 s23, s23, 0
	global_load_dword v33, v0, s[22:23]
	s_add_u32 s22, s22, 0x6000
	s_addc_u32 s23, s23, 0
	ds_read_b128 v[98:101], v1 offset:0
	ds_read_b128 v[102:105], v1 offset:4096
	ds_read_b128 v[106:109], v1 offset:8192
	ds_read_b128 v[110:113], v1 offset:12288
	ds_read_b128 v[114:117], v1 offset:16384
	ds_read_b128 v[118:121], v1 offset:20480
	ds_read_b128 v[122:125], v1 offset:24576
	ds_read_b128 v[126:129], v1 offset:28672
	ds_read_b128 v[130:133], v1 offset:32768
	global_load_dword v34, v0, s[22:23]
	s_add_u32 s22, s22, 0x6000
	s_addc_u32 s23, s23, 0
	global_load_dword v35, v0, s[22:23]
	s_add_u32 s22, s22, 0x6000
	s_addc_u32 s23, s23, 0
	global_load_dword v36, v0, s[22:23]
	s_add_u32 s22, s22, 0x6000
	s_addc_u32 s23, s23, 0
	global_load_dword v37, v0, s[22:23]
	s_add_u32 s22, s22, 0x6000
	s_addc_u32 s23, s23, 0
	global_load_dword v38, v0, s[22:23]
	s_add_u32 s22, s22, 0x6000
	s_addc_u32 s23, s23, 0
	global_load_dword v39, v0, s[22:23]
	s_add_u32 s22, s22, 0x6000
	s_addc_u32 s23, s23, 0
	global_load_dword v40, v0, s[22:23]
	s_add_u32 s22, s22, 0x6000
	s_addc_u32 s23, s23, 0
	global_load_dword v41, v0, s[22:23]
	s_add_u32 s22, s22, 0x6000
	s_addc_u32 s23, s23, 0
	global_load_dword v42, v0, s[22:23]
	s_add_u32 s22, s22, 0x6000
	s_addc_u32 s23, s23, 0
	global_load_dword v43, v0, s[22:23]
	s_add_u32 s22, s22, 0x6000
	s_addc_u32 s23, s23, 0
	global_load_dword v44, v0, s[22:23]
	s_add_u32 s22, s22, 0x6000
	s_addc_u32 s23, s23, 0
	global_load_dword v45, v0, s[22:23]
	s_add_u32 s22, s22, 0x6000
	s_addc_u32 s23, s23, 0
	global_load_dword v46, v0, s[22:23]
	s_add_u32 s22, s22, 0x6000
	s_addc_u32 s23, s23, 0
	global_load_dword v47, v0, s[22:23]
	s_add_u32 s22, s22, 0x6000
	s_addc_u32 s23, s23, 0
	global_load_dword v48, v0, s[22:23]
	s_add_u32 s22, s22, 0x6000
	s_addc_u32 s23, s23, 0
	global_load_dword v49, v0, s[22:23]
	s_add_u32 s22, s22, 0x6000
	s_addc_u32 s23, s23, 0
	global_load_dword v50, v0, s[22:23]
	s_add_u32 s22, s22, 0x6000
	s_addc_u32 s23, s23, 0
	global_load_dword v51, v0, s[22:23]
	s_add_u32 s22, s22, 0x6000
	s_addc_u32 s23, s23, 0
; #define LAS __attribute__((address_space(3)))
; __device__ __forceinline__ void prologue(const __attribute__((address_space(4))) Args& a, ldsp lds, int gw, int NGW, int wave, int lane, const int tid, const int bid, const int G) {
;     ...
;         for (int k = wave * 128; k < wave * 128 + 128; k += 16) {
;             float wv[16];
; #pragma unroll
;             for (int q = 0; q < 16; ++q) wv[q] = Wl[(size_t)(k + q) * NMOD];
; #pragma unroll
;             for (int q4 = 0; q4 < 4; ++q4)
; #pragma unroll
;                 for (int j = 0; j < 9; ++j) { const f32x4 s4 = *(const LAS f32x4*)(sc + j * D + k + 4 * q4); acc[j] += s4[0] * wv[4 * q4] + s4[1] * wv[4 * q4 + 1] + s4[2] * wv[4 * q4 + 2] + s4[3] * wv[4 * q4 + 3]; }
	global_load_dword v52, v0, s[22:23]
	s_add_u32 s22, s22, 0x6000
	s_addc_u32 s23, s23, 0
	global_load_dword v53, v0, s[22:23]
	s_add_u32 s22, s22, 0x6000
	s_addc_u32 s23, s23, 0
	global_load_dword v54, v0, s[22:23]
	s_add_u32 s22, s22, 0x6000
	s_addc_u32 s23, s23, 0
	global_load_dword v55, v0, s[22:23]
	s_add_u32 s22, s22, 0x6000
	s_addc_u32 s23, s23, 0
	global_load_dword v56, v0, s[22:23]
	s_add_u32 s22, s22, 0x6000
	s_addc_u32 s23, s23, 0
	global_load_dword v57, v0, s[22:23]
	s_add_u32 s22, s22, 0x6000
	s_addc_u32 s23, s23, 0
	global_load_dword v58, v0, s[22:23]
	s_add_u32 s22, s22, 0x6000
	s_addc_u32 s23, s23, 0
	global_load_dword v59, v0, s[22:23]
	s_add_u32 s22, s22, 0x6000
	s_addc_u32 s23, s23, 0
	global_load_dword v60, v0, s[22:23]
	s_add_u32 s22, s22, 0x6000
	s_addc_u32 s23, s23, 0
	global_load_dword v61, v0, s[22:23]
	s_add_u32 s22, s22, 0x6000
	s_addc_u32 s23, s23, 0
	global_load_dword v62, v0, s[22:23]
	s_add_u32 s22, s22, 0x6000
	s_addc_u32 s23, s23, 0
	global_load_dword v63, v0, s[22:23]
	s_add_u32 s22, s22, 0x6000
	s_addc_u32 s23, s23, 0
	global_load_dword v64, v0, s[22:23]
	s_add_u32 s22, s22, 0x6000
	s_addc_u32 s23, s23, 0
	global_load_dword v65, v0, s[22:23]
	s_add_u32 s22, s22, 0x6000
	s_addc_u32 s23, s23, 0
	v_mov_b64_e32 v[226:227], 0
	v_mov_b64_e32 v[228:229], 0
	v_mov_b64_e32 v[230:231], 0
	v_mov_b64_e32 v[232:233], 0
	v_mov_b64_e32 v[234:235], 0
	v_mov_b64_e32 v[236:237], 0
	v_mov_b64_e32 v[238:239], 0
	v_mov_b64_e32 v[240:241], 0
	v_mov_b64_e32 v[242:243], 0
	s_waitcnt vmcnt(32)
	ds_read_b128 v[134:137], v1 offset:16
	ds_read_b128 v[138:141], v1 offset:4112
	ds_read_b128 v[142:145], v1 offset:8208
	ds_read_b128 v[146:149], v1 offset:12304
	ds_read_b128 v[150:153], v1 offset:16400
	ds_read_b128 v[154:157], v1 offset:20496
	ds_read_b128 v[158:161], v1 offset:24592
	ds_read_b128 v[162:165], v1 offset:28688
	ds_read_b128 v[166:169], v1 offset:32784
	s_waitcnt lgkmcnt(9)
	v_pk_fma_f32 v[226:227], v[98:99], v[2:3], v[226:227]
	v_pk_fma_f32 v[228:229], v[102:103], v[2:3], v[228:229]
	v_pk_fma_f32 v[230:231], v[106:107], v[2:3], v[230:231]
	v_pk_fma_f32 v[232:233], v[110:111], v[2:3], v[232:233]
	v_pk_fma_f32 v[234:235], v[114:115], v[2:3], v[234:235]
	v_pk_fma_f32 v[236:237], v[118:119], v[2:3], v[236:237]
	v_pk_fma_f32 v[238:239], v[122:123], v[2:3], v[238:239]
	v_pk_fma_f32 v[240:241], v[126:127], v[2:3], v[240:241]
	v_pk_fma_f32 v[242:243], v[130:131], v[2:3], v[242:243]
	v_pk_fma_f32 v[226:227], v[100:101], v[4:5], v[226:227]
	v_pk_fma_f32 v[228:229], v[104:105], v[4:5], v[228:229]
	v_pk_fma_f32 v[230:231], v[108:109], v[4:5], v[230:231]
	v_pk_fma_f32 v[232:233], v[112:113], v[4:5], v[232:233]
	v_pk_fma_f32 v[234:235], v[116:117], v[4:5], v[234:235]
	v_pk_fma_f32 v[236:237], v[120:121], v[4:5], v[236:237]
	v_pk_fma_f32 v[238:239], v[124:125], v[4:5], v[238:239]
	v_pk_fma_f32 v[240:241], v[128:129], v[4:5], v[240:241]
	v_pk_fma_f32 v[242:243], v[132:133], v[4:5], v[242:243]
	ds_read_b128 v[98:101], v1 offset:32
	ds_read_b128 v[102:105], v1 offset:4128
	ds_read_b128 v[106:109], v1 offset:8224
	ds_read_b128 v[110:113], v1 offset:12320
	ds_read_b128 v[114:117], v1 offset:16416
	ds_read_b128 v[118:121], v1 offset:20512
	ds_read_b128 v[122:125], v1 offset:24608
	ds_read_b128 v[126:129], v1 offset:28704
	ds_read_b128 v[130:133], v1 offset:32800
	s_waitcnt lgkmcnt(9)
	v_pk_fma_f32 v[226:227], v[134:135], v[6:7], v[226:227]
	v_pk_fma_f32 v[228:229], v[138:139], v[6:7], v[228:229]
	v_pk_fma_f32 v[230:231], v[142:143], v[6:7], v[230:231]
	v_pk_fma_f32 v[232:233], v[146:147], v[6:7], v[232:233]
	v_pk_fma_f32 v[234:235], v[150:151], v[6:7], v[234:235]
	v_pk_fma_f32 v[236:237], v[154:155], v[6:7], v[236:237]
	v_pk_fma_f32 v[238:239], v[158:159], v[6:7], v[238:239]
	v_pk_fma_f32 v[240:241], v[162:163], v[6:7], v[240:241]
	v_pk_fma_f32 v[242:243], v[166:167], v[6:7], v[242:243]
	v_pk_fma_f32 v[226:227], v[136:137], v[8:9], v[226:227]
	v_pk_fma_f32 v[228:229], v[140:141], v[8:9], v[228:229]
	v_pk_fma_f32 v[230:231], v[144:145], v[8:9], v[230:231]
	v_pk_fma_f32 v[232:233], v[148:149], v[8:9], v[232:233]
	v_pk_fma_f32 v[234:235], v[152:153], v[8:9], v[234:235]
	v_pk_fma_f32 v[236:237], v[156:157], v[8:9], v[236:237]
	v_pk_fma_f32 v[238:239], v[160:161], v[8:9], v[238:239]
	v_pk_fma_f32 v[240:241], v[164:165], v[8:9], v[240:241]
	v_pk_fma_f32 v[242:243], v[168:169], v[8:9], v[242:243]
	ds_read_b128 v[134:137], v1 offset:48
	ds_read_b128 v[138:141], v1 offset:4144
	ds_read_b128 v[142:145], v1 offset:8240
	ds_read_b128 v[146:149], v1 offset:12336
	ds_read_b128 v[150:153], v1 offset:16432
	ds_read_b128 v[154:157], v1 offset:20528
	ds_read_b128 v[158:161], v1 offset:24624
	ds_read_b128 v[162:165], v1 offset:28720
	ds_read_b128 v[166:169], v1 offset:32816
	s_waitcnt lgkmcnt(9)
	v_pk_fma_f32 v[226:227], v[98:99], v[10:11], v[226:227]
	v_pk_fma_f32 v[228:229], v[102:103], v[10:11], v[228:229]
	v_pk_fma_f32 v[230:231], v[106:107], v[10:11], v[230:231]
	v_pk_fma_f32 v[232:233], v[110:111], v[10:11], v[232:233]
	v_pk_fma_f32 v[234:235], v[114:115], v[10:11], v[234:235]
	v_pk_fma_f32 v[236:237], v[118:119], v[10:11], v[236:237]
	v_pk_fma_f32 v[238:239], v[122:123], v[10:11], v[238:239]
	v_pk_fma_f32 v[240:241], v[126:127], v[10:11], v[240:241]
	v_pk_fma_f32 v[242:243], v[130:131], v[10:11], v[242:243]
	v_pk_fma_f32 v[226:227], v[100:101], v[12:13], v[226:227]
	v_pk_fma_f32 v[228:229], v[104:105], v[12:13], v[228:229]
	v_pk_fma_f32 v[230:231], v[108:109], v[12:13], v[230:231]
	v_pk_fma_f32 v[232:233], v[112:113], v[12:13], v[232:233]
	v_pk_fma_f32 v[234:235], v[116:117], v[12:13], v[234:235]
	v_pk_fma_f32 v[236:237], v[120:121], v[12:13], v[236:237]
	v_pk_fma_f32 v[238:239], v[124:125], v[12:13], v[238:239]
	v_pk_fma_f32 v[240:241], v[128:129], v[12:13], v[240:241]
	v_pk_fma_f32 v[242:243], v[132:133], v[12:13], v[242:243]
	ds_read_b128 v[98:101], v1 offset:64
	ds_read_b128 v[102:105], v1 offset:4160
	ds_read_b128 v[106:109], v1 offset:8256
	ds_read_b128 v[110:113], v1 offset:12352
	ds_read_b128 v[114:117], v1 offset:16448
	ds_read_b128 v[118:121], v1 offset:20544
	ds_read_b128 v[122:125], v1 offset:24640
	ds_read_b128 v[126:129], v1 offset:28736
	ds_read_b128 v[130:133], v1 offset:32832
	s_waitcnt lgkmcnt(9)
; #define LAS __attribute__((address_space(3)))
; __device__ __forceinline__ void prologue(const __attribute__((address_space(4))) Args& a, ldsp lds, int gw, int NGW, int wave, int lane, const int tid, const int bid, const int G) {
;     ...
;         for (int k = wave * 128; k < wave * 128 + 128; k += 16) {
;             float wv[16];
; #pragma unroll
;             for (int q = 0; q < 16; ++q) wv[q] = Wl[(size_t)(k + q) * NMOD];
; #pragma unroll
;             for (int q4 = 0; q4 < 4; ++q4)
; #pragma unroll
;                 for (int j = 0; j < 9; ++j) { const f32x4 s4 = *(const LAS f32x4*)(sc + j * D + k + 4 * q4); acc[j] += s4[0] * wv[4 * q4] + s4[1] * wv[4 * q4 + 1] + s4[2] * wv[4 * q4 + 2] + s4[3] * wv[4 * q4 + 3]; }
	v_pk_fma_f32 v[226:227], v[134:135], v[14:15], v[226:227]
	v_pk_fma_f32 v[228:229], v[138:139], v[14:15], v[228:229]
	v_pk_fma_f32 v[230:231], v[142:143], v[14:15], v[230:231]
	v_pk_fma_f32 v[232:233], v[146:147], v[14:15], v[232:233]
	v_pk_fma_f32 v[234:235], v[150:151], v[14:15], v[234:235]
	v_pk_fma_f32 v[236:237], v[154:155], v[14:15], v[236:237]
	v_pk_fma_f32 v[238:239], v[158:159], v[14:15], v[238:239]
	v_pk_fma_f32 v[240:241], v[162:163], v[14:15], v[240:241]
	v_pk_fma_f32 v[242:243], v[166:167], v[14:15], v[242:243]
	v_pk_fma_f32 v[226:227], v[136:137], v[16:17], v[226:227]
	v_pk_fma_f32 v[228:229], v[140:141], v[16:17], v[228:229]
	v_pk_fma_f32 v[230:231], v[144:145], v[16:17], v[230:231]
	v_pk_fma_f32 v[232:233], v[148:149], v[16:17], v[232:233]
	v_pk_fma_f32 v[234:235], v[152:153], v[16:17], v[234:235]
	v_pk_fma_f32 v[236:237], v[156:157], v[16:17], v[236:237]
	v_pk_fma_f32 v[238:239], v[160:161], v[16:17], v[238:239]
	v_pk_fma_f32 v[240:241], v[164:165], v[16:17], v[240:241]
	v_pk_fma_f32 v[242:243], v[168:169], v[16:17], v[242:243]
	ds_read_b128 v[134:137], v1 offset:80
	ds_read_b128 v[138:141], v1 offset:4176
	ds_read_b128 v[142:145], v1 offset:8272
	ds_read_b128 v[146:149], v1 offset:12368
	ds_read_b128 v[150:153], v1 offset:16464
	ds_read_b128 v[154:157], v1 offset:20560
	ds_read_b128 v[158:161], v1 offset:24656
	ds_read_b128 v[162:165], v1 offset:28752
	ds_read_b128 v[166:169], v1 offset:32848
	s_waitcnt lgkmcnt(9)
	v_pk_fma_f32 v[226:227], v[98:99], v[18:19], v[226:227]
	v_pk_fma_f32 v[228:229], v[102:103], v[18:19], v[228:229]
	v_pk_fma_f32 v[230:231], v[106:107], v[18:19], v[230:231]
	v_pk_fma_f32 v[232:233], v[110:111], v[18:19], v[232:233]
	v_pk_fma_f32 v[234:235], v[114:115], v[18:19], v[234:235]
	v_pk_fma_f32 v[236:237], v[118:119], v[18:19], v[236:237]
	v_pk_fma_f32 v[238:239], v[122:123], v[18:19], v[238:239]
	v_pk_fma_f32 v[240:241], v[126:127], v[18:19], v[240:241]
	v_pk_fma_f32 v[242:243], v[130:131], v[18:19], v[242:243]
	v_pk_fma_f32 v[226:227], v[100:101], v[20:21], v[226:227]
	v_pk_fma_f32 v[228:229], v[104:105], v[20:21], v[228:229]
	v_pk_fma_f32 v[230:231], v[108:109], v[20:21], v[230:231]
	v_pk_fma_f32 v[232:233], v[112:113], v[20:21], v[232:233]
	v_pk_fma_f32 v[234:235], v[116:117], v[20:21], v[234:235]
	v_pk_fma_f32 v[236:237], v[120:121], v[20:21], v[236:237]
	v_pk_fma_f32 v[238:239], v[124:125], v[20:21], v[238:239]
	v_pk_fma_f32 v[240:241], v[128:129], v[20:21], v[240:241]
	v_pk_fma_f32 v[242:243], v[132:133], v[20:21], v[242:243]
	ds_read_b128 v[98:101], v1 offset:96
	ds_read_b128 v[102:105], v1 offset:4192
	ds_read_b128 v[106:109], v1 offset:8288
	ds_read_b128 v[110:113], v1 offset:12384
	ds_read_b128 v[114:117], v1 offset:16480
	ds_read_b128 v[118:121], v1 offset:20576
	ds_read_b128 v[122:125], v1 offset:24672
	ds_read_b128 v[126:129], v1 offset:28768
	ds_read_b128 v[130:133], v1 offset:32864
	s_waitcnt lgkmcnt(9)
	v_pk_fma_f32 v[226:227], v[134:135], v[22:23], v[226:227]
	v_pk_fma_f32 v[228:229], v[138:139], v[22:23], v[228:229]
	v_pk_fma_f32 v[230:231], v[142:143], v[22:23], v[230:231]
	v_pk_fma_f32 v[232:233], v[146:147], v[22:23], v[232:233]
	v_pk_fma_f32 v[234:235], v[150:151], v[22:23], v[234:235]
	v_pk_fma_f32 v[236:237], v[154:155], v[22:23], v[236:237]
	v_pk_fma_f32 v[238:239], v[158:159], v[22:23], v[238:239]
	v_pk_fma_f32 v[240:241], v[162:163], v[22:23], v[240:241]
	v_pk_fma_f32 v[242:243], v[166:167], v[22:23], v[242:243]
	v_pk_fma_f32 v[226:227], v[136:137], v[24:25], v[226:227]
	v_pk_fma_f32 v[228:229], v[140:141], v[24:25], v[228:229]
	v_pk_fma_f32 v[230:231], v[144:145], v[24:25], v[230:231]
	v_pk_fma_f32 v[232:233], v[148:149], v[24:25], v[232:233]
	v_pk_fma_f32 v[234:235], v[152:153], v[24:25], v[234:235]
	v_pk_fma_f32 v[236:237], v[156:157], v[24:25], v[236:237]
	v_pk_fma_f32 v[238:239], v[160:161], v[24:25], v[238:239]
	v_pk_fma_f32 v[240:241], v[164:165], v[24:25], v[240:241]
	v_pk_fma_f32 v[242:243], v[168:169], v[24:25], v[242:243]
	ds_read_b128 v[134:137], v1 offset:112
	ds_read_b128 v[138:141], v1 offset:4208
	ds_read_b128 v[142:145], v1 offset:8304
	ds_read_b128 v[146:149], v1 offset:12400
	ds_read_b128 v[150:153], v1 offset:16496
	ds_read_b128 v[154:157], v1 offset:20592
	ds_read_b128 v[158:161], v1 offset:24688
	ds_read_b128 v[162:165], v1 offset:28784
	ds_read_b128 v[166:169], v1 offset:32880
	s_waitcnt lgkmcnt(9)
	v_pk_fma_f32 v[226:227], v[98:99], v[26:27], v[226:227]
	v_pk_fma_f32 v[228:229], v[102:103], v[26:27], v[228:229]
	v_pk_fma_f32 v[230:231], v[106:107], v[26:27], v[230:231]
	v_pk_fma_f32 v[232:233], v[110:111], v[26:27], v[232:233]
	v_pk_fma_f32 v[234:235], v[114:115], v[26:27], v[234:235]
	v_pk_fma_f32 v[236:237], v[118:119], v[26:27], v[236:237]
	v_pk_fma_f32 v[238:239], v[122:123], v[26:27], v[238:239]
	v_pk_fma_f32 v[240:241], v[126:127], v[26:27], v[240:241]
	v_pk_fma_f32 v[242:243], v[130:131], v[26:27], v[242:243]
	v_pk_fma_f32 v[226:227], v[100:101], v[28:29], v[226:227]
	v_pk_fma_f32 v[228:229], v[104:105], v[28:29], v[228:229]
	v_pk_fma_f32 v[230:231], v[108:109], v[28:29], v[230:231]
	v_pk_fma_f32 v[232:233], v[112:113], v[28:29], v[232:233]
	v_pk_fma_f32 v[234:235], v[116:117], v[28:29], v[234:235]
	v_pk_fma_f32 v[236:237], v[120:121], v[28:29], v[236:237]
	v_pk_fma_f32 v[238:239], v[124:125], v[28:29], v[238:239]
	v_pk_fma_f32 v[240:241], v[128:129], v[28:29], v[240:241]
	v_pk_fma_f32 v[242:243], v[132:133], v[28:29], v[242:243]
	ds_read_b128 v[98:101], v1 offset:128
	ds_read_b128 v[102:105], v1 offset:4224
	ds_read_b128 v[106:109], v1 offset:8320
	ds_read_b128 v[110:113], v1 offset:12416
	ds_read_b128 v[114:117], v1 offset:16512
	ds_read_b128 v[118:121], v1 offset:20608
	ds_read_b128 v[122:125], v1 offset:24704
	ds_read_b128 v[126:129], v1 offset:28800
	ds_read_b128 v[130:133], v1 offset:32896
	s_waitcnt lgkmcnt(9)
; #define LAS __attribute__((address_space(3)))
; __device__ __forceinline__ void prologue(const __attribute__((address_space(4))) Args& a, ldsp lds, int gw, int NGW, int wave, int lane, const int tid, const int bid, const int G) {
;     ...
;         for (int k = wave * 128; k < wave * 128 + 128; k += 16) {
;             float wv[16];
; #pragma unroll
;             for (int q = 0; q < 16; ++q) wv[q] = Wl[(size_t)(k + q) * NMOD];
; #pragma unroll
;             for (int q4 = 0; q4 < 4; ++q4)
; #pragma unroll
;                 for (int j = 0; j < 9; ++j) { const f32x4 s4 = *(const LAS f32x4*)(sc + j * D + k + 4 * q4); acc[j] += s4[0] * wv[4 * q4] + s4[1] * wv[4 * q4 + 1] + s4[2] * wv[4 * q4 + 2] + s4[3] * wv[4 * q4 + 3]; }
	v_pk_fma_f32 v[226:227], v[134:135], v[30:31], v[226:227]
	v_pk_fma_f32 v[228:229], v[138:139], v[30:31], v[228:229]
	v_pk_fma_f32 v[230:231], v[142:143], v[30:31], v[230:231]
	v_pk_fma_f32 v[232:233], v[146:147], v[30:31], v[232:233]
	v_pk_fma_f32 v[234:235], v[150:151], v[30:31], v[234:235]
	v_pk_fma_f32 v[236:237], v[154:155], v[30:31], v[236:237]
	v_pk_fma_f32 v[238:239], v[158:159], v[30:31], v[238:239]
	v_pk_fma_f32 v[240:241], v[162:163], v[30:31], v[240:241]
	v_pk_fma_f32 v[242:243], v[166:167], v[30:31], v[242:243]
	v_pk_fma_f32 v[226:227], v[136:137], v[32:33], v[226:227]
	v_pk_fma_f32 v[228:229], v[140:141], v[32:33], v[228:229]
	v_pk_fma_f32 v[230:231], v[144:145], v[32:33], v[230:231]
	v_pk_fma_f32 v[232:233], v[148:149], v[32:33], v[232:233]
	v_pk_fma_f32 v[234:235], v[152:153], v[32:33], v[234:235]
	v_pk_fma_f32 v[236:237], v[156:157], v[32:33], v[236:237]
	v_pk_fma_f32 v[238:239], v[160:161], v[32:33], v[238:239]
	v_pk_fma_f32 v[240:241], v[164:165], v[32:33], v[240:241]
	v_pk_fma_f32 v[242:243], v[168:169], v[32:33], v[242:243]
	global_load_dword v2, v0, s[22:23]
	s_add_u32 s22, s22, 0x6000
	s_addc_u32 s23, s23, 0
	global_load_dword v3, v0, s[22:23]
	s_add_u32 s22, s22, 0x6000
	s_addc_u32 s23, s23, 0
	global_load_dword v4, v0, s[22:23]
	s_add_u32 s22, s22, 0x6000
	s_addc_u32 s23, s23, 0
	global_load_dword v5, v0, s[22:23]
	s_add_u32 s22, s22, 0x6000
	s_addc_u32 s23, s23, 0
	global_load_dword v6, v0, s[22:23]
	s_add_u32 s22, s22, 0x6000
	s_addc_u32 s23, s23, 0
	global_load_dword v7, v0, s[22:23]
	s_add_u32 s22, s22, 0x6000
	s_addc_u32 s23, s23, 0
	global_load_dword v8, v0, s[22:23]
	s_add_u32 s22, s22, 0x6000
	s_addc_u32 s23, s23, 0
	global_load_dword v9, v0, s[22:23]
	s_add_u32 s22, s22, 0x6000
	s_addc_u32 s23, s23, 0
	global_load_dword v10, v0, s[22:23]
	s_add_u32 s22, s22, 0x6000
	s_addc_u32 s23, s23, 0
	global_load_dword v11, v0, s[22:23]
	s_add_u32 s22, s22, 0x6000
	s_addc_u32 s23, s23, 0
	global_load_dword v12, v0, s[22:23]
	s_add_u32 s22, s22, 0x6000
	s_addc_u32 s23, s23, 0
	global_load_dword v13, v0, s[22:23]
	s_add_u32 s22, s22, 0x6000
	s_addc_u32 s23, s23, 0
	global_load_dword v14, v0, s[22:23]
	s_add_u32 s22, s22, 0x6000
	s_addc_u32 s23, s23, 0
	global_load_dword v15, v0, s[22:23]
	s_add_u32 s22, s22, 0x6000
	s_addc_u32 s23, s23, 0
	global_load_dword v16, v0, s[22:23]
	s_add_u32 s22, s22, 0x6000
	s_addc_u32 s23, s23, 0
	global_load_dword v17, v0, s[22:23]
	s_add_u32 s22, s22, 0x6000
	s_addc_u32 s23, s23, 0
	global_load_dword v18, v0, s[22:23]
	s_add_u32 s22, s22, 0x6000
	s_addc_u32 s23, s23, 0
	global_load_dword v19, v0, s[22:23]
	s_add_u32 s22, s22, 0x6000
	s_addc_u32 s23, s23, 0
	global_load_dword v20, v0, s[22:23]
	s_add_u32 s22, s22, 0x6000
	s_addc_u32 s23, s23, 0
	global_load_dword v21, v0, s[22:23]
	s_add_u32 s22, s22, 0x6000
	s_addc_u32 s23, s23, 0
	global_load_dword v22, v0, s[22:23]
	s_add_u32 s22, s22, 0x6000
	s_addc_u32 s23, s23, 0
	global_load_dword v23, v0, s[22:23]
	s_add_u32 s22, s22, 0x6000
	s_addc_u32 s23, s23, 0
	global_load_dword v24, v0, s[22:23]
	s_add_u32 s22, s22, 0x6000
	s_addc_u32 s23, s23, 0
	global_load_dword v25, v0, s[22:23]
	s_add_u32 s22, s22, 0x6000
	s_addc_u32 s23, s23, 0
	global_load_dword v26, v0, s[22:23]
	s_add_u32 s22, s22, 0x6000
	s_addc_u32 s23, s23, 0
	global_load_dword v27, v0, s[22:23]
	s_add_u32 s22, s22, 0x6000
	s_addc_u32 s23, s23, 0
	global_load_dword v28, v0, s[22:23]
	s_add_u32 s22, s22, 0x6000
	s_addc_u32 s23, s23, 0
	global_load_dword v29, v0, s[22:23]
	s_add_u32 s22, s22, 0x6000
	s_addc_u32 s23, s23, 0
	global_load_dword v30, v0, s[22:23]
	s_add_u32 s22, s22, 0x6000
	s_addc_u32 s23, s23, 0
	global_load_dword v31, v0, s[22:23]
	s_add_u32 s22, s22, 0x6000
	s_addc_u32 s23, s23, 0
	global_load_dword v32, v0, s[22:23]
	s_add_u32 s22, s22, 0x6000
	s_addc_u32 s23, s23, 0
	global_load_dword v33, v0, s[22:23]
	s_add_u32 s22, s22, 0x6000
	s_addc_u32 s23, s23, 0
	s_waitcnt vmcnt(32)
	ds_read_b128 v[134:137], v1 offset:144
	ds_read_b128 v[138:141], v1 offset:4240
	ds_read_b128 v[142:145], v1 offset:8336
	ds_read_b128 v[146:149], v1 offset:12432
	ds_read_b128 v[150:153], v1 offset:16528
	ds_read_b128 v[154:157], v1 offset:20624
	ds_read_b128 v[158:161], v1 offset:24720
	ds_read_b128 v[162:165], v1 offset:28816
	ds_read_b128 v[166:169], v1 offset:32912
	s_waitcnt lgkmcnt(9)
	v_pk_fma_f32 v[226:227], v[98:99], v[34:35], v[226:227]
	v_pk_fma_f32 v[228:229], v[102:103], v[34:35], v[228:229]
	v_pk_fma_f32 v[230:231], v[106:107], v[34:35], v[230:231]
	v_pk_fma_f32 v[232:233], v[110:111], v[34:35], v[232:233]
	v_pk_fma_f32 v[234:235], v[114:115], v[34:35], v[234:235]
	v_pk_fma_f32 v[236:237], v[118:119], v[34:35], v[236:237]
	v_pk_fma_f32 v[238:239], v[122:123], v[34:35], v[238:239]
	v_pk_fma_f32 v[240:241], v[126:127], v[34:35], v[240:241]
	v_pk_fma_f32 v[242:243], v[130:131], v[34:35], v[242:243]
	v_pk_fma_f32 v[226:227], v[100:101], v[36:37], v[226:227]
	v_pk_fma_f32 v[228:229], v[104:105], v[36:37], v[228:229]
	v_pk_fma_f32 v[230:231], v[108:109], v[36:37], v[230:231]
	v_pk_fma_f32 v[232:233], v[112:113], v[36:37], v[232:233]
	v_pk_fma_f32 v[234:235], v[116:117], v[36:37], v[234:235]
	v_pk_fma_f32 v[236:237], v[120:121], v[36:37], v[236:237]
	v_pk_fma_f32 v[238:239], v[124:125], v[36:37], v[238:239]
	v_pk_fma_f32 v[240:241], v[128:129], v[36:37], v[240:241]
	v_pk_fma_f32 v[242:243], v[132:133], v[36:37], v[242:243]
	ds_read_b128 v[98:101], v1 offset:160
	ds_read_b128 v[102:105], v1 offset:4256
	ds_read_b128 v[106:109], v1 offset:8352
	ds_read_b128 v[110:113], v1 offset:12448
	ds_read_b128 v[114:117], v1 offset:16544
	ds_read_b128 v[118:121], v1 offset:20640
	ds_read_b128 v[122:125], v1 offset:24736
	ds_read_b128 v[126:129], v1 offset:28832
	ds_read_b128 v[130:133], v1 offset:32928
	s_waitcnt lgkmcnt(9)
; #define LAS __attribute__((address_space(3)))
; __device__ __forceinline__ void prologue(const __attribute__((address_space(4))) Args& a, ldsp lds, int gw, int NGW, int wave, int lane, const int tid, const int bid, const int G) {
;     ...
;         for (int k = wave * 128; k < wave * 128 + 128; k += 16) {
;             float wv[16];
; #pragma unroll
;             for (int q = 0; q < 16; ++q) wv[q] = Wl[(size_t)(k + q) * NMOD];
; #pragma unroll
;             for (int q4 = 0; q4 < 4; ++q4)
; #pragma unroll
;                 for (int j = 0; j < 9; ++j) { const f32x4 s4 = *(const LAS f32x4*)(sc + j * D + k + 4 * q4); acc[j] += s4[0] * wv[4 * q4] + s4[1] * wv[4 * q4 + 1] + s4[2] * wv[4 * q4 + 2] + s4[3] * wv[4 * q4 + 3]; }
	v_pk_fma_f32 v[226:227], v[134:135], v[38:39], v[226:227]
	v_pk_fma_f32 v[228:229], v[138:139], v[38:39], v[228:229]
	v_pk_fma_f32 v[230:231], v[142:143], v[38:39], v[230:231]
	v_pk_fma_f32 v[232:233], v[146:147], v[38:39], v[232:233]
	v_pk_fma_f32 v[234:235], v[150:151], v[38:39], v[234:235]
	v_pk_fma_f32 v[236:237], v[154:155], v[38:39], v[236:237]
	v_pk_fma_f32 v[238:239], v[158:159], v[38:39], v[238:239]
	v_pk_fma_f32 v[240:241], v[162:163], v[38:39], v[240:241]
	v_pk_fma_f32 v[242:243], v[166:167], v[38:39], v[242:243]
	v_pk_fma_f32 v[226:227], v[136:137], v[40:41], v[226:227]
	v_pk_fma_f32 v[228:229], v[140:141], v[40:41], v[228:229]
	v_pk_fma_f32 v[230:231], v[144:145], v[40:41], v[230:231]
	v_pk_fma_f32 v[232:233], v[148:149], v[40:41], v[232:233]
	v_pk_fma_f32 v[234:235], v[152:153], v[40:41], v[234:235]
	v_pk_fma_f32 v[236:237], v[156:157], v[40:41], v[236:237]
	v_pk_fma_f32 v[238:239], v[160:161], v[40:41], v[238:239]
	v_pk_fma_f32 v[240:241], v[164:165], v[40:41], v[240:241]
	v_pk_fma_f32 v[242:243], v[168:169], v[40:41], v[242:243]
	ds_read_b128 v[134:137], v1 offset:176
	ds_read_b128 v[138:141], v1 offset:4272
	ds_read_b128 v[142:145], v1 offset:8368
	ds_read_b128 v[146:149], v1 offset:12464
	ds_read_b128 v[150:153], v1 offset:16560
	ds_read_b128 v[154:157], v1 offset:20656
	ds_read_b128 v[158:161], v1 offset:24752
	ds_read_b128 v[162:165], v1 offset:28848
	ds_read_b128 v[166:169], v1 offset:32944
	s_waitcnt lgkmcnt(9)
	v_pk_fma_f32 v[226:227], v[98:99], v[42:43], v[226:227]
	v_pk_fma_f32 v[228:229], v[102:103], v[42:43], v[228:229]
	v_pk_fma_f32 v[230:231], v[106:107], v[42:43], v[230:231]
	v_pk_fma_f32 v[232:233], v[110:111], v[42:43], v[232:233]
	v_pk_fma_f32 v[234:235], v[114:115], v[42:43], v[234:235]
	v_pk_fma_f32 v[236:237], v[118:119], v[42:43], v[236:237]
	v_pk_fma_f32 v[238:239], v[122:123], v[42:43], v[238:239]
	v_pk_fma_f32 v[240:241], v[126:127], v[42:43], v[240:241]
	v_pk_fma_f32 v[242:243], v[130:131], v[42:43], v[242:243]
	v_pk_fma_f32 v[226:227], v[100:101], v[44:45], v[226:227]
	v_pk_fma_f32 v[228:229], v[104:105], v[44:45], v[228:229]
	v_pk_fma_f32 v[230:231], v[108:109], v[44:45], v[230:231]
	v_pk_fma_f32 v[232:233], v[112:113], v[44:45], v[232:233]
	v_pk_fma_f32 v[234:235], v[116:117], v[44:45], v[234:235]
	v_pk_fma_f32 v[236:237], v[120:121], v[44:45], v[236:237]
	v_pk_fma_f32 v[238:239], v[124:125], v[44:45], v[238:239]
	v_pk_fma_f32 v[240:241], v[128:129], v[44:45], v[240:241]
	v_pk_fma_f32 v[242:243], v[132:133], v[44:45], v[242:243]
	ds_read_b128 v[98:101], v1 offset:192
	ds_read_b128 v[102:105], v1 offset:4288
	ds_read_b128 v[106:109], v1 offset:8384
	ds_read_b128 v[110:113], v1 offset:12480
	ds_read_b128 v[114:117], v1 offset:16576
	ds_read_b128 v[118:121], v1 offset:20672
	ds_read_b128 v[122:125], v1 offset:24768
	ds_read_b128 v[126:129], v1 offset:28864
	ds_read_b128 v[130:133], v1 offset:32960
	s_waitcnt lgkmcnt(9)
	v_pk_fma_f32 v[226:227], v[134:135], v[46:47], v[226:227]
	v_pk_fma_f32 v[228:229], v[138:139], v[46:47], v[228:229]
	v_pk_fma_f32 v[230:231], v[142:143], v[46:47], v[230:231]
	v_pk_fma_f32 v[232:233], v[146:147], v[46:47], v[232:233]
	v_pk_fma_f32 v[234:235], v[150:151], v[46:47], v[234:235]
	v_pk_fma_f32 v[236:237], v[154:155], v[46:47], v[236:237]
	v_pk_fma_f32 v[238:239], v[158:159], v[46:47], v[238:239]
	v_pk_fma_f32 v[240:241], v[162:163], v[46:47], v[240:241]
	v_pk_fma_f32 v[242:243], v[166:167], v[46:47], v[242:243]
	v_pk_fma_f32 v[226:227], v[136:137], v[48:49], v[226:227]
	v_pk_fma_f32 v[228:229], v[140:141], v[48:49], v[228:229]
	v_pk_fma_f32 v[230:231], v[144:145], v[48:49], v[230:231]
	v_pk_fma_f32 v[232:233], v[148:149], v[48:49], v[232:233]
	v_pk_fma_f32 v[234:235], v[152:153], v[48:49], v[234:235]
	v_pk_fma_f32 v[236:237], v[156:157], v[48:49], v[236:237]
	v_pk_fma_f32 v[238:239], v[160:161], v[48:49], v[238:239]
	v_pk_fma_f32 v[240:241], v[164:165], v[48:49], v[240:241]
	v_pk_fma_f32 v[242:243], v[168:169], v[48:49], v[242:243]
	ds_read_b128 v[134:137], v1 offset:208
	ds_read_b128 v[138:141], v1 offset:4304
	ds_read_b128 v[142:145], v1 offset:8400
	ds_read_b128 v[146:149], v1 offset:12496
	ds_read_b128 v[150:153], v1 offset:16592
	ds_read_b128 v[154:157], v1 offset:20688
	ds_read_b128 v[158:161], v1 offset:24784
	ds_read_b128 v[162:165], v1 offset:28880
	ds_read_b128 v[166:169], v1 offset:32976
	s_waitcnt lgkmcnt(9)
	v_pk_fma_f32 v[226:227], v[98:99], v[50:51], v[226:227]
	v_pk_fma_f32 v[228:229], v[102:103], v[50:51], v[228:229]
	v_pk_fma_f32 v[230:231], v[106:107], v[50:51], v[230:231]
	v_pk_fma_f32 v[232:233], v[110:111], v[50:51], v[232:233]
	v_pk_fma_f32 v[234:235], v[114:115], v[50:51], v[234:235]
	v_pk_fma_f32 v[236:237], v[118:119], v[50:51], v[236:237]
	v_pk_fma_f32 v[238:239], v[122:123], v[50:51], v[238:239]
	v_pk_fma_f32 v[240:241], v[126:127], v[50:51], v[240:241]
	v_pk_fma_f32 v[242:243], v[130:131], v[50:51], v[242:243]
	v_pk_fma_f32 v[226:227], v[100:101], v[52:53], v[226:227]
	v_pk_fma_f32 v[228:229], v[104:105], v[52:53], v[228:229]
	v_pk_fma_f32 v[230:231], v[108:109], v[52:53], v[230:231]
	v_pk_fma_f32 v[232:233], v[112:113], v[52:53], v[232:233]
	v_pk_fma_f32 v[234:235], v[116:117], v[52:53], v[234:235]
	v_pk_fma_f32 v[236:237], v[120:121], v[52:53], v[236:237]
	v_pk_fma_f32 v[238:239], v[124:125], v[52:53], v[238:239]
	v_pk_fma_f32 v[240:241], v[128:129], v[52:53], v[240:241]
	v_pk_fma_f32 v[242:243], v[132:133], v[52:53], v[242:243]
	ds_read_b128 v[98:101], v1 offset:224
	ds_read_b128 v[102:105], v1 offset:4320
	ds_read_b128 v[106:109], v1 offset:8416
	ds_read_b128 v[110:113], v1 offset:12512
	ds_read_b128 v[114:117], v1 offset:16608
	ds_read_b128 v[118:121], v1 offset:20704
	ds_read_b128 v[122:125], v1 offset:24800
	ds_read_b128 v[126:129], v1 offset:28896
	ds_read_b128 v[130:133], v1 offset:32992
	s_waitcnt lgkmcnt(9)
; #define LAS __attribute__((address_space(3)))
; __device__ __forceinline__ void prologue(const __attribute__((address_space(4))) Args& a, ldsp lds, int gw, int NGW, int wave, int lane, const int tid, const int bid, const int G) {
;     ...
;         for (int k = wave * 128; k < wave * 128 + 128; k += 16) {
;             float wv[16];
; #pragma unroll
;             for (int q = 0; q < 16; ++q) wv[q] = Wl[(size_t)(k + q) * NMOD];
; #pragma unroll
;             for (int q4 = 0; q4 < 4; ++q4)
; #pragma unroll
;                 for (int j = 0; j < 9; ++j) { const f32x4 s4 = *(const LAS f32x4*)(sc + j * D + k + 4 * q4); acc[j] += s4[0] * wv[4 * q4] + s4[1] * wv[4 * q4 + 1] + s4[2] * wv[4 * q4 + 2] + s4[3] * wv[4 * q4 + 3]; }
	v_pk_fma_f32 v[226:227], v[134:135], v[54:55], v[226:227]
	v_pk_fma_f32 v[228:229], v[138:139], v[54:55], v[228:229]
	v_pk_fma_f32 v[230:231], v[142:143], v[54:55], v[230:231]
	v_pk_fma_f32 v[232:233], v[146:147], v[54:55], v[232:233]
	v_pk_fma_f32 v[234:235], v[150:151], v[54:55], v[234:235]
	v_pk_fma_f32 v[236:237], v[154:155], v[54:55], v[236:237]
	v_pk_fma_f32 v[238:239], v[158:159], v[54:55], v[238:239]
	v_pk_fma_f32 v[240:241], v[162:163], v[54:55], v[240:241]
	v_pk_fma_f32 v[242:243], v[166:167], v[54:55], v[242:243]
	v_pk_fma_f32 v[226:227], v[136:137], v[56:57], v[226:227]
	v_pk_fma_f32 v[228:229], v[140:141], v[56:57], v[228:229]
	v_pk_fma_f32 v[230:231], v[144:145], v[56:57], v[230:231]
	v_pk_fma_f32 v[232:233], v[148:149], v[56:57], v[232:233]
	v_pk_fma_f32 v[234:235], v[152:153], v[56:57], v[234:235]
	v_pk_fma_f32 v[236:237], v[156:157], v[56:57], v[236:237]
	v_pk_fma_f32 v[238:239], v[160:161], v[56:57], v[238:239]
	v_pk_fma_f32 v[240:241], v[164:165], v[56:57], v[240:241]
	v_pk_fma_f32 v[242:243], v[168:169], v[56:57], v[242:243]
	ds_read_b128 v[134:137], v1 offset:240
	ds_read_b128 v[138:141], v1 offset:4336
	ds_read_b128 v[142:145], v1 offset:8432
	ds_read_b128 v[146:149], v1 offset:12528
	ds_read_b128 v[150:153], v1 offset:16624
	ds_read_b128 v[154:157], v1 offset:20720
	ds_read_b128 v[158:161], v1 offset:24816
	ds_read_b128 v[162:165], v1 offset:28912
	ds_read_b128 v[166:169], v1 offset:33008
	s_waitcnt lgkmcnt(9)
	v_pk_fma_f32 v[226:227], v[98:99], v[58:59], v[226:227]
	v_pk_fma_f32 v[228:229], v[102:103], v[58:59], v[228:229]
	v_pk_fma_f32 v[230:231], v[106:107], v[58:59], v[230:231]
	v_pk_fma_f32 v[232:233], v[110:111], v[58:59], v[232:233]
	v_pk_fma_f32 v[234:235], v[114:115], v[58:59], v[234:235]
	v_pk_fma_f32 v[236:237], v[118:119], v[58:59], v[236:237]
	v_pk_fma_f32 v[238:239], v[122:123], v[58:59], v[238:239]
	v_pk_fma_f32 v[240:241], v[126:127], v[58:59], v[240:241]
	v_pk_fma_f32 v[242:243], v[130:131], v[58:59], v[242:243]
	v_pk_fma_f32 v[226:227], v[100:101], v[60:61], v[226:227]
	v_pk_fma_f32 v[228:229], v[104:105], v[60:61], v[228:229]
	v_pk_fma_f32 v[230:231], v[108:109], v[60:61], v[230:231]
	v_pk_fma_f32 v[232:233], v[112:113], v[60:61], v[232:233]
	v_pk_fma_f32 v[234:235], v[116:117], v[60:61], v[234:235]
	v_pk_fma_f32 v[236:237], v[120:121], v[60:61], v[236:237]
	v_pk_fma_f32 v[238:239], v[124:125], v[60:61], v[238:239]
	v_pk_fma_f32 v[240:241], v[128:129], v[60:61], v[240:241]
	v_pk_fma_f32 v[242:243], v[132:133], v[60:61], v[242:243]
	ds_read_b128 v[98:101], v1 offset:256
	ds_read_b128 v[102:105], v1 offset:4352
	ds_read_b128 v[106:109], v1 offset:8448
	ds_read_b128 v[110:113], v1 offset:12544
	ds_read_b128 v[114:117], v1 offset:16640
	ds_read_b128 v[118:121], v1 offset:20736
	ds_read_b128 v[122:125], v1 offset:24832
	ds_read_b128 v[126:129], v1 offset:28928
	ds_read_b128 v[130:133], v1 offset:33024
	s_waitcnt lgkmcnt(9)
	v_pk_fma_f32 v[226:227], v[134:135], v[62:63], v[226:227]
	v_pk_fma_f32 v[228:229], v[138:139], v[62:63], v[228:229]
	v_pk_fma_f32 v[230:231], v[142:143], v[62:63], v[230:231]
	v_pk_fma_f32 v[232:233], v[146:147], v[62:63], v[232:233]
	v_pk_fma_f32 v[234:235], v[150:151], v[62:63], v[234:235]
	v_pk_fma_f32 v[236:237], v[154:155], v[62:63], v[236:237]
	v_pk_fma_f32 v[238:239], v[158:159], v[62:63], v[238:239]
	v_pk_fma_f32 v[240:241], v[162:163], v[62:63], v[240:241]
	v_pk_fma_f32 v[242:243], v[166:167], v[62:63], v[242:243]
	v_pk_fma_f32 v[226:227], v[136:137], v[64:65], v[226:227]
	v_pk_fma_f32 v[228:229], v[140:141], v[64:65], v[228:229]
	v_pk_fma_f32 v[230:231], v[144:145], v[64:65], v[230:231]
	v_pk_fma_f32 v[232:233], v[148:149], v[64:65], v[232:233]
	v_pk_fma_f32 v[234:235], v[152:153], v[64:65], v[234:235]
	v_pk_fma_f32 v[236:237], v[156:157], v[64:65], v[236:237]
	v_pk_fma_f32 v[238:239], v[160:161], v[64:65], v[238:239]
	v_pk_fma_f32 v[240:241], v[164:165], v[64:65], v[240:241]
	v_pk_fma_f32 v[242:243], v[168:169], v[64:65], v[242:243]
	global_load_dword v34, v0, s[22:23]
	s_add_u32 s22, s22, 0x6000
	s_addc_u32 s23, s23, 0
	global_load_dword v35, v0, s[22:23]
	s_add_u32 s22, s22, 0x6000
	s_addc_u32 s23, s23, 0
	global_load_dword v36, v0, s[22:23]
	s_add_u32 s22, s22, 0x6000
	s_addc_u32 s23, s23, 0
	global_load_dword v37, v0, s[22:23]
	s_add_u32 s22, s22, 0x6000
	s_addc_u32 s23, s23, 0
	global_load_dword v38, v0, s[22:23]
	s_add_u32 s22, s22, 0x6000
	s_addc_u32 s23, s23, 0
	global_load_dword v39, v0, s[22:23]
	s_add_u32 s22, s22, 0x6000
	s_addc_u32 s23, s23, 0
	global_load_dword v40, v0, s[22:23]
	s_add_u32 s22, s22, 0x6000
	s_addc_u32 s23, s23, 0
	global_load_dword v41, v0, s[22:23]
	s_add_u32 s22, s22, 0x6000
	s_addc_u32 s23, s23, 0
	global_load_dword v42, v0, s[22:23]
	s_add_u32 s22, s22, 0x6000
	s_addc_u32 s23, s23, 0
	global_load_dword v43, v0, s[22:23]
	s_add_u32 s22, s22, 0x6000
	s_addc_u32 s23, s23, 0
	global_load_dword v44, v0, s[22:23]
	s_add_u32 s22, s22, 0x6000
	s_addc_u32 s23, s23, 0
	global_load_dword v45, v0, s[22:23]
	s_add_u32 s22, s22, 0x6000
	s_addc_u32 s23, s23, 0
	global_load_dword v46, v0, s[22:23]
	s_add_u32 s22, s22, 0x6000
	s_addc_u32 s23, s23, 0
	global_load_dword v47, v0, s[22:23]
	s_add_u32 s22, s22, 0x6000
	s_addc_u32 s23, s23, 0
	global_load_dword v48, v0, s[22:23]
	s_add_u32 s22, s22, 0x6000
	s_addc_u32 s23, s23, 0
	global_load_dword v49, v0, s[22:23]
	s_add_u32 s22, s22, 0x6000
	s_addc_u32 s23, s23, 0
	global_load_dword v50, v0, s[22:23]
	s_add_u32 s22, s22, 0x6000
	s_addc_u32 s23, s23, 0
	global_load_dword v51, v0, s[22:23]
	s_add_u32 s22, s22, 0x6000
	s_addc_u32 s23, s23, 0
	global_load_dword v52, v0, s[22:23]
	s_add_u32 s22, s22, 0x6000
	s_addc_u32 s23, s23, 0
	global_load_dword v53, v0, s[22:23]
	s_add_u32 s22, s22, 0x6000
	s_addc_u32 s23, s23, 0
	global_load_dword v54, v0, s[22:23]
	s_add_u32 s22, s22, 0x6000
	s_addc_u32 s23, s23, 0
	global_load_dword v55, v0, s[22:23]
	s_add_u32 s22, s22, 0x6000
	s_addc_u32 s23, s23, 0
	global_load_dword v56, v0, s[22:23]
	s_add_u32 s22, s22, 0x6000
	s_addc_u32 s23, s23, 0
	global_load_dword v57, v0, s[22:23]
	s_add_u32 s22, s22, 0x6000
	s_addc_u32 s23, s23, 0
	global_load_dword v58, v0, s[22:23]
	s_add_u32 s22, s22, 0x6000
	s_addc_u32 s23, s23, 0
	global_load_dword v59, v0, s[22:23]
	s_add_u32 s22, s22, 0x6000
	s_addc_u32 s23, s23, 0
	global_load_dword v60, v0, s[22:23]
	s_add_u32 s22, s22, 0x6000
	s_addc_u32 s23, s23, 0
	global_load_dword v61, v0, s[22:23]
	s_add_u32 s22, s22, 0x6000
	s_addc_u32 s23, s23, 0
	global_load_dword v62, v0, s[22:23]
	s_add_u32 s22, s22, 0x6000
	s_addc_u32 s23, s23, 0
	global_load_dword v63, v0, s[22:23]
	s_add_u32 s22, s22, 0x6000
	s_addc_u32 s23, s23, 0
	global_load_dword v64, v0, s[22:23]
	s_add_u32 s22, s22, 0x6000
	s_addc_u32 s23, s23, 0
	global_load_dword v65, v0, s[22:23]
	s_add_u32 s22, s22, 0x6000
	s_addc_u32 s23, s23, 0
	s_waitcnt vmcnt(32)
; #define LAS __attribute__((address_space(3)))
; __device__ __forceinline__ void prologue(const __attribute__((address_space(4))) Args& a, ldsp lds, int gw, int NGW, int wave, int lane, const int tid, const int bid, const int G) {
;     ...
;         for (int k = wave * 128; k < wave * 128 + 128; k += 16) {
;             float wv[16];
; #pragma unroll
;             for (int q = 0; q < 16; ++q) wv[q] = Wl[(size_t)(k + q) * NMOD];
; #pragma unroll
;             for (int q4 = 0; q4 < 4; ++q4)
; #pragma unroll
;                 for (int j = 0; j < 9; ++j) { const f32x4 s4 = *(const LAS f32x4*)(sc + j * D + k + 4 * q4); acc[j] += s4[0] * wv[4 * q4] + s4[1] * wv[4 * q4 + 1] + s4[2] * wv[4 * q4 + 2] + s4[3] * wv[4 * q4 + 3]; }
	ds_read_b128 v[134:137], v1 offset:272
	ds_read_b128 v[138:141], v1 offset:4368
	ds_read_b128 v[142:145], v1 offset:8464
	ds_read_b128 v[146:149], v1 offset:12560
	ds_read_b128 v[150:153], v1 offset:16656
	ds_read_b128 v[154:157], v1 offset:20752
	ds_read_b128 v[158:161], v1 offset:24848
	ds_read_b128 v[162:165], v1 offset:28944
	ds_read_b128 v[166:169], v1 offset:33040
	s_waitcnt lgkmcnt(9)
	v_pk_fma_f32 v[226:227], v[98:99], v[2:3], v[226:227]
	v_pk_fma_f32 v[228:229], v[102:103], v[2:3], v[228:229]
	v_pk_fma_f32 v[230:231], v[106:107], v[2:3], v[230:231]
	v_pk_fma_f32 v[232:233], v[110:111], v[2:3], v[232:233]
	v_pk_fma_f32 v[234:235], v[114:115], v[2:3], v[234:235]
	v_pk_fma_f32 v[236:237], v[118:119], v[2:3], v[236:237]
	v_pk_fma_f32 v[238:239], v[122:123], v[2:3], v[238:239]
	v_pk_fma_f32 v[240:241], v[126:127], v[2:3], v[240:241]
	v_pk_fma_f32 v[242:243], v[130:131], v[2:3], v[242:243]
	v_pk_fma_f32 v[226:227], v[100:101], v[4:5], v[226:227]
	v_pk_fma_f32 v[228:229], v[104:105], v[4:5], v[228:229]
	v_pk_fma_f32 v[230:231], v[108:109], v[4:5], v[230:231]
	v_pk_fma_f32 v[232:233], v[112:113], v[4:5], v[232:233]
	v_pk_fma_f32 v[234:235], v[116:117], v[4:5], v[234:235]
	v_pk_fma_f32 v[236:237], v[120:121], v[4:5], v[236:237]
	v_pk_fma_f32 v[238:239], v[124:125], v[4:5], v[238:239]
	v_pk_fma_f32 v[240:241], v[128:129], v[4:5], v[240:241]
	v_pk_fma_f32 v[242:243], v[132:133], v[4:5], v[242:243]
	ds_read_b128 v[98:101], v1 offset:288
	ds_read_b128 v[102:105], v1 offset:4384
	ds_read_b128 v[106:109], v1 offset:8480
	ds_read_b128 v[110:113], v1 offset:12576
	ds_read_b128 v[114:117], v1 offset:16672
	ds_read_b128 v[118:121], v1 offset:20768
	ds_read_b128 v[122:125], v1 offset:24864
	ds_read_b128 v[126:129], v1 offset:28960
	ds_read_b128 v[130:133], v1 offset:33056
	s_waitcnt lgkmcnt(9)
	v_pk_fma_f32 v[226:227], v[134:135], v[6:7], v[226:227]
	v_pk_fma_f32 v[228:229], v[138:139], v[6:7], v[228:229]
	v_pk_fma_f32 v[230:231], v[142:143], v[6:7], v[230:231]
	v_pk_fma_f32 v[232:233], v[146:147], v[6:7], v[232:233]
	v_pk_fma_f32 v[234:235], v[150:151], v[6:7], v[234:235]
	v_pk_fma_f32 v[236:237], v[154:155], v[6:7], v[236:237]
	v_pk_fma_f32 v[238:239], v[158:159], v[6:7], v[238:239]
	v_pk_fma_f32 v[240:241], v[162:163], v[6:7], v[240:241]
	v_pk_fma_f32 v[242:243], v[166:167], v[6:7], v[242:243]
	v_pk_fma_f32 v[226:227], v[136:137], v[8:9], v[226:227]
	v_pk_fma_f32 v[228:229], v[140:141], v[8:9], v[228:229]
	v_pk_fma_f32 v[230:231], v[144:145], v[8:9], v[230:231]
	v_pk_fma_f32 v[232:233], v[148:149], v[8:9], v[232:233]
	v_pk_fma_f32 v[234:235], v[152:153], v[8:9], v[234:235]
	v_pk_fma_f32 v[236:237], v[156:157], v[8:9], v[236:237]
	v_pk_fma_f32 v[238:239], v[160:161], v[8:9], v[238:239]
	v_pk_fma_f32 v[240:241], v[164:165], v[8:9], v[240:241]
	v_pk_fma_f32 v[242:243], v[168:169], v[8:9], v[242:243]
	ds_read_b128 v[134:137], v1 offset:304
	ds_read_b128 v[138:141], v1 offset:4400
	ds_read_b128 v[142:145], v1 offset:8496
	ds_read_b128 v[146:149], v1 offset:12592
	ds_read_b128 v[150:153], v1 offset:16688
	ds_read_b128 v[154:157], v1 offset:20784
	ds_read_b128 v[158:161], v1 offset:24880
	ds_read_b128 v[162:165], v1 offset:28976
	ds_read_b128 v[166:169], v1 offset:33072
	s_waitcnt lgkmcnt(9)
	v_pk_fma_f32 v[226:227], v[98:99], v[10:11], v[226:227]
	v_pk_fma_f32 v[228:229], v[102:103], v[10:11], v[228:229]
	v_pk_fma_f32 v[230:231], v[106:107], v[10:11], v[230:231]
	v_pk_fma_f32 v[232:233], v[110:111], v[10:11], v[232:233]
	v_pk_fma_f32 v[234:235], v[114:115], v[10:11], v[234:235]
	v_pk_fma_f32 v[236:237], v[118:119], v[10:11], v[236:237]
	v_pk_fma_f32 v[238:239], v[122:123], v[10:11], v[238:239]
	v_pk_fma_f32 v[240:241], v[126:127], v[10:11], v[240:241]
	v_pk_fma_f32 v[242:243], v[130:131], v[10:11], v[242:243]
	v_pk_fma_f32 v[226:227], v[100:101], v[12:13], v[226:227]
	v_pk_fma_f32 v[228:229], v[104:105], v[12:13], v[228:229]
	v_pk_fma_f32 v[230:231], v[108:109], v[12:13], v[230:231]
	v_pk_fma_f32 v[232:233], v[112:113], v[12:13], v[232:233]
	v_pk_fma_f32 v[234:235], v[116:117], v[12:13], v[234:235]
	v_pk_fma_f32 v[236:237], v[120:121], v[12:13], v[236:237]
	v_pk_fma_f32 v[238:239], v[124:125], v[12:13], v[238:239]
	v_pk_fma_f32 v[240:241], v[128:129], v[12:13], v[240:241]
	v_pk_fma_f32 v[242:243], v[132:133], v[12:13], v[242:243]
	ds_read_b128 v[98:101], v1 offset:320
	ds_read_b128 v[102:105], v1 offset:4416
	ds_read_b128 v[106:109], v1 offset:8512
	ds_read_b128 v[110:113], v1 offset:12608
	ds_read_b128 v[114:117], v1 offset:16704
	ds_read_b128 v[118:121], v1 offset:20800
	ds_read_b128 v[122:125], v1 offset:24896
	ds_read_b128 v[126:129], v1 offset:28992
	ds_read_b128 v[130:133], v1 offset:33088
	s_waitcnt lgkmcnt(9)
	v_pk_fma_f32 v[226:227], v[134:135], v[14:15], v[226:227]
	v_pk_fma_f32 v[228:229], v[138:139], v[14:15], v[228:229]
	v_pk_fma_f32 v[230:231], v[142:143], v[14:15], v[230:231]
	v_pk_fma_f32 v[232:233], v[146:147], v[14:15], v[232:233]
	v_pk_fma_f32 v[234:235], v[150:151], v[14:15], v[234:235]
	v_pk_fma_f32 v[236:237], v[154:155], v[14:15], v[236:237]
	v_pk_fma_f32 v[238:239], v[158:159], v[14:15], v[238:239]
	v_pk_fma_f32 v[240:241], v[162:163], v[14:15], v[240:241]
	v_pk_fma_f32 v[242:243], v[166:167], v[14:15], v[242:243]
	v_pk_fma_f32 v[226:227], v[136:137], v[16:17], v[226:227]
	v_pk_fma_f32 v[228:229], v[140:141], v[16:17], v[228:229]
	v_pk_fma_f32 v[230:231], v[144:145], v[16:17], v[230:231]
	v_pk_fma_f32 v[232:233], v[148:149], v[16:17], v[232:233]
	v_pk_fma_f32 v[234:235], v[152:153], v[16:17], v[234:235]
	v_pk_fma_f32 v[236:237], v[156:157], v[16:17], v[236:237]
	v_pk_fma_f32 v[238:239], v[160:161], v[16:17], v[238:239]
	v_pk_fma_f32 v[240:241], v[164:165], v[16:17], v[240:241]
	v_pk_fma_f32 v[242:243], v[168:169], v[16:17], v[242:243]
	ds_read_b128 v[134:137], v1 offset:336
	ds_read_b128 v[138:141], v1 offset:4432
	ds_read_b128 v[142:145], v1 offset:8528
	ds_read_b128 v[146:149], v1 offset:12624
	ds_read_b128 v[150:153], v1 offset:16720
	ds_read_b128 v[154:157], v1 offset:20816
	ds_read_b128 v[158:161], v1 offset:24912
	ds_read_b128 v[162:165], v1 offset:29008
	ds_read_b128 v[166:169], v1 offset:33104
	s_waitcnt lgkmcnt(9)
; #define LAS __attribute__((address_space(3)))
; __device__ __forceinline__ void prologue(const __attribute__((address_space(4))) Args& a, ldsp lds, int gw, int NGW, int wave, int lane, const int tid, const int bid, const int G) {
;     ...
;         for (int k = wave * 128; k < wave * 128 + 128; k += 16) {
;             float wv[16];
; #pragma unroll
;             for (int q = 0; q < 16; ++q) wv[q] = Wl[(size_t)(k + q) * NMOD];
; #pragma unroll
;             for (int q4 = 0; q4 < 4; ++q4)
; #pragma unroll
;                 for (int j = 0; j < 9; ++j) { const f32x4 s4 = *(const LAS f32x4*)(sc + j * D + k + 4 * q4); acc[j] += s4[0] * wv[4 * q4] + s4[1] * wv[4 * q4 + 1] + s4[2] * wv[4 * q4 + 2] + s4[3] * wv[4 * q4 + 3]; }
	v_pk_fma_f32 v[226:227], v[98:99], v[18:19], v[226:227]
	v_pk_fma_f32 v[228:229], v[102:103], v[18:19], v[228:229]
	v_pk_fma_f32 v[230:231], v[106:107], v[18:19], v[230:231]
	v_pk_fma_f32 v[232:233], v[110:111], v[18:19], v[232:233]
	v_pk_fma_f32 v[234:235], v[114:115], v[18:19], v[234:235]
	v_pk_fma_f32 v[236:237], v[118:119], v[18:19], v[236:237]
	v_pk_fma_f32 v[238:239], v[122:123], v[18:19], v[238:239]
	v_pk_fma_f32 v[240:241], v[126:127], v[18:19], v[240:241]
	v_pk_fma_f32 v[242:243], v[130:131], v[18:19], v[242:243]
	v_pk_fma_f32 v[226:227], v[100:101], v[20:21], v[226:227]
	v_pk_fma_f32 v[228:229], v[104:105], v[20:21], v[228:229]
	v_pk_fma_f32 v[230:231], v[108:109], v[20:21], v[230:231]
	v_pk_fma_f32 v[232:233], v[112:113], v[20:21], v[232:233]
	v_pk_fma_f32 v[234:235], v[116:117], v[20:21], v[234:235]
	v_pk_fma_f32 v[236:237], v[120:121], v[20:21], v[236:237]
	v_pk_fma_f32 v[238:239], v[124:125], v[20:21], v[238:239]
	v_pk_fma_f32 v[240:241], v[128:129], v[20:21], v[240:241]
	v_pk_fma_f32 v[242:243], v[132:133], v[20:21], v[242:243]
	ds_read_b128 v[98:101], v1 offset:352
	ds_read_b128 v[102:105], v1 offset:4448
	ds_read_b128 v[106:109], v1 offset:8544
	ds_read_b128 v[110:113], v1 offset:12640
	ds_read_b128 v[114:117], v1 offset:16736
	ds_read_b128 v[118:121], v1 offset:20832
	ds_read_b128 v[122:125], v1 offset:24928
	ds_read_b128 v[126:129], v1 offset:29024
	ds_read_b128 v[130:133], v1 offset:33120
	s_waitcnt lgkmcnt(9)
	v_pk_fma_f32 v[226:227], v[134:135], v[22:23], v[226:227]
	v_pk_fma_f32 v[228:229], v[138:139], v[22:23], v[228:229]
	v_pk_fma_f32 v[230:231], v[142:143], v[22:23], v[230:231]
	v_pk_fma_f32 v[232:233], v[146:147], v[22:23], v[232:233]
	v_pk_fma_f32 v[234:235], v[150:151], v[22:23], v[234:235]
	v_pk_fma_f32 v[236:237], v[154:155], v[22:23], v[236:237]
	v_pk_fma_f32 v[238:239], v[158:159], v[22:23], v[238:239]
	v_pk_fma_f32 v[240:241], v[162:163], v[22:23], v[240:241]
	v_pk_fma_f32 v[242:243], v[166:167], v[22:23], v[242:243]
	v_pk_fma_f32 v[226:227], v[136:137], v[24:25], v[226:227]
	v_pk_fma_f32 v[228:229], v[140:141], v[24:25], v[228:229]
	v_pk_fma_f32 v[230:231], v[144:145], v[24:25], v[230:231]
	v_pk_fma_f32 v[232:233], v[148:149], v[24:25], v[232:233]
	v_pk_fma_f32 v[234:235], v[152:153], v[24:25], v[234:235]
	v_pk_fma_f32 v[236:237], v[156:157], v[24:25], v[236:237]
	v_pk_fma_f32 v[238:239], v[160:161], v[24:25], v[238:239]
	v_pk_fma_f32 v[240:241], v[164:165], v[24:25], v[240:241]
	v_pk_fma_f32 v[242:243], v[168:169], v[24:25], v[242:243]
	ds_read_b128 v[134:137], v1 offset:368
	ds_read_b128 v[138:141], v1 offset:4464
	ds_read_b128 v[142:145], v1 offset:8560
	ds_read_b128 v[146:149], v1 offset:12656
	ds_read_b128 v[150:153], v1 offset:16752
	ds_read_b128 v[154:157], v1 offset:20848
	ds_read_b128 v[158:161], v1 offset:24944
	ds_read_b128 v[162:165], v1 offset:29040
	ds_read_b128 v[166:169], v1 offset:33136
	s_waitcnt lgkmcnt(9)
	v_pk_fma_f32 v[226:227], v[98:99], v[26:27], v[226:227]
	v_pk_fma_f32 v[228:229], v[102:103], v[26:27], v[228:229]
	v_pk_fma_f32 v[230:231], v[106:107], v[26:27], v[230:231]
	v_pk_fma_f32 v[232:233], v[110:111], v[26:27], v[232:233]
	v_pk_fma_f32 v[234:235], v[114:115], v[26:27], v[234:235]
	v_pk_fma_f32 v[236:237], v[118:119], v[26:27], v[236:237]
	v_pk_fma_f32 v[238:239], v[122:123], v[26:27], v[238:239]
	v_pk_fma_f32 v[240:241], v[126:127], v[26:27], v[240:241]
	v_pk_fma_f32 v[242:243], v[130:131], v[26:27], v[242:243]
	v_pk_fma_f32 v[226:227], v[100:101], v[28:29], v[226:227]
	v_pk_fma_f32 v[228:229], v[104:105], v[28:29], v[228:229]
	v_pk_fma_f32 v[230:231], v[108:109], v[28:29], v[230:231]
	v_pk_fma_f32 v[232:233], v[112:113], v[28:29], v[232:233]
	v_pk_fma_f32 v[234:235], v[116:117], v[28:29], v[234:235]
	v_pk_fma_f32 v[236:237], v[120:121], v[28:29], v[236:237]
	v_pk_fma_f32 v[238:239], v[124:125], v[28:29], v[238:239]
	v_pk_fma_f32 v[240:241], v[128:129], v[28:29], v[240:241]
	v_pk_fma_f32 v[242:243], v[132:133], v[28:29], v[242:243]
	ds_read_b128 v[98:101], v1 offset:384
	ds_read_b128 v[102:105], v1 offset:4480
	ds_read_b128 v[106:109], v1 offset:8576
	ds_read_b128 v[110:113], v1 offset:12672
	ds_read_b128 v[114:117], v1 offset:16768
	ds_read_b128 v[118:121], v1 offset:20864
	ds_read_b128 v[122:125], v1 offset:24960
	ds_read_b128 v[126:129], v1 offset:29056
	ds_read_b128 v[130:133], v1 offset:33152
	s_waitcnt lgkmcnt(9)
	v_pk_fma_f32 v[226:227], v[134:135], v[30:31], v[226:227]
	v_pk_fma_f32 v[228:229], v[138:139], v[30:31], v[228:229]
	v_pk_fma_f32 v[230:231], v[142:143], v[30:31], v[230:231]
	v_pk_fma_f32 v[232:233], v[146:147], v[30:31], v[232:233]
	v_pk_fma_f32 v[234:235], v[150:151], v[30:31], v[234:235]
	v_pk_fma_f32 v[236:237], v[154:155], v[30:31], v[236:237]
	v_pk_fma_f32 v[238:239], v[158:159], v[30:31], v[238:239]
	v_pk_fma_f32 v[240:241], v[162:163], v[30:31], v[240:241]
	v_pk_fma_f32 v[242:243], v[166:167], v[30:31], v[242:243]
	v_pk_fma_f32 v[226:227], v[136:137], v[32:33], v[226:227]
	v_pk_fma_f32 v[228:229], v[140:141], v[32:33], v[228:229]
	v_pk_fma_f32 v[230:231], v[144:145], v[32:33], v[230:231]
	v_pk_fma_f32 v[232:233], v[148:149], v[32:33], v[232:233]
	v_pk_fma_f32 v[234:235], v[152:153], v[32:33], v[234:235]
	v_pk_fma_f32 v[236:237], v[156:157], v[32:33], v[236:237]
	v_pk_fma_f32 v[238:239], v[160:161], v[32:33], v[238:239]
	v_pk_fma_f32 v[240:241], v[164:165], v[32:33], v[240:241]
	v_pk_fma_f32 v[242:243], v[168:169], v[32:33], v[242:243]
	s_waitcnt vmcnt(0)
; #define LAS __attribute__((address_space(3)))
; __device__ __forceinline__ void prologue(const __attribute__((address_space(4))) Args& a, ldsp lds, int gw, int NGW, int wave, int lane, const int tid, const int bid, const int G) {
;     ...
;         for (int k = wave * 128; k < wave * 128 + 128; k += 16) {
;             float wv[16];
; #pragma unroll
;             for (int q = 0; q < 16; ++q) wv[q] = Wl[(size_t)(k + q) * NMOD];
; #pragma unroll
;             for (int q4 = 0; q4 < 4; ++q4)
; #pragma unroll
;                 for (int j = 0; j < 9; ++j) { const f32x4 s4 = *(const LAS f32x4*)(sc + j * D + k + 4 * q4); acc[j] += s4[0] * wv[4 * q4] + s4[1] * wv[4 * q4 + 1] + s4[2] * wv[4 * q4 + 2] + s4[3] * wv[4 * q4 + 3]; }
	ds_read_b128 v[134:137], v1 offset:400
	ds_read_b128 v[138:141], v1 offset:4496
	ds_read_b128 v[142:145], v1 offset:8592
	ds_read_b128 v[146:149], v1 offset:12688
	ds_read_b128 v[150:153], v1 offset:16784
	ds_read_b128 v[154:157], v1 offset:20880
	ds_read_b128 v[158:161], v1 offset:24976
	ds_read_b128 v[162:165], v1 offset:29072
	ds_read_b128 v[166:169], v1 offset:33168
	s_waitcnt lgkmcnt(9)
	v_pk_fma_f32 v[226:227], v[98:99], v[34:35], v[226:227]
	v_pk_fma_f32 v[228:229], v[102:103], v[34:35], v[228:229]
	v_pk_fma_f32 v[230:231], v[106:107], v[34:35], v[230:231]
	v_pk_fma_f32 v[232:233], v[110:111], v[34:35], v[232:233]
	v_pk_fma_f32 v[234:235], v[114:115], v[34:35], v[234:235]
	v_pk_fma_f32 v[236:237], v[118:119], v[34:35], v[236:237]
	v_pk_fma_f32 v[238:239], v[122:123], v[34:35], v[238:239]
	v_pk_fma_f32 v[240:241], v[126:127], v[34:35], v[240:241]
	v_pk_fma_f32 v[242:243], v[130:131], v[34:35], v[242:243]
	v_pk_fma_f32 v[226:227], v[100:101], v[36:37], v[226:227]
	v_pk_fma_f32 v[228:229], v[104:105], v[36:37], v[228:229]
	v_pk_fma_f32 v[230:231], v[108:109], v[36:37], v[230:231]
	v_pk_fma_f32 v[232:233], v[112:113], v[36:37], v[232:233]
	v_pk_fma_f32 v[234:235], v[116:117], v[36:37], v[234:235]
	v_pk_fma_f32 v[236:237], v[120:121], v[36:37], v[236:237]
	v_pk_fma_f32 v[238:239], v[124:125], v[36:37], v[238:239]
	v_pk_fma_f32 v[240:241], v[128:129], v[36:37], v[240:241]
	v_pk_fma_f32 v[242:243], v[132:133], v[36:37], v[242:243]
	ds_read_b128 v[98:101], v1 offset:416
	ds_read_b128 v[102:105], v1 offset:4512
	ds_read_b128 v[106:109], v1 offset:8608
	ds_read_b128 v[110:113], v1 offset:12704
	ds_read_b128 v[114:117], v1 offset:16800
	ds_read_b128 v[118:121], v1 offset:20896
	ds_read_b128 v[122:125], v1 offset:24992
	ds_read_b128 v[126:129], v1 offset:29088
	ds_read_b128 v[130:133], v1 offset:33184
	s_waitcnt lgkmcnt(9)
	v_pk_fma_f32 v[226:227], v[134:135], v[38:39], v[226:227]
	v_pk_fma_f32 v[228:229], v[138:139], v[38:39], v[228:229]
	v_pk_fma_f32 v[230:231], v[142:143], v[38:39], v[230:231]
	v_pk_fma_f32 v[232:233], v[146:147], v[38:39], v[232:233]
	v_pk_fma_f32 v[234:235], v[150:151], v[38:39], v[234:235]
	v_pk_fma_f32 v[236:237], v[154:155], v[38:39], v[236:237]
	v_pk_fma_f32 v[238:239], v[158:159], v[38:39], v[238:239]
	v_pk_fma_f32 v[240:241], v[162:163], v[38:39], v[240:241]
	v_pk_fma_f32 v[242:243], v[166:167], v[38:39], v[242:243]
	v_pk_fma_f32 v[226:227], v[136:137], v[40:41], v[226:227]
	v_pk_fma_f32 v[228:229], v[140:141], v[40:41], v[228:229]
	v_pk_fma_f32 v[230:231], v[144:145], v[40:41], v[230:231]
	v_pk_fma_f32 v[232:233], v[148:149], v[40:41], v[232:233]
	v_pk_fma_f32 v[234:235], v[152:153], v[40:41], v[234:235]
	v_pk_fma_f32 v[236:237], v[156:157], v[40:41], v[236:237]
	v_pk_fma_f32 v[238:239], v[160:161], v[40:41], v[238:239]
	v_pk_fma_f32 v[240:241], v[164:165], v[40:41], v[240:241]
	v_pk_fma_f32 v[242:243], v[168:169], v[40:41], v[242:243]
	ds_read_b128 v[134:137], v1 offset:432
	ds_read_b128 v[138:141], v1 offset:4528
	ds_read_b128 v[142:145], v1 offset:8624
	ds_read_b128 v[146:149], v1 offset:12720
	ds_read_b128 v[150:153], v1 offset:16816
	ds_read_b128 v[154:157], v1 offset:20912
	ds_read_b128 v[158:161], v1 offset:25008
	ds_read_b128 v[162:165], v1 offset:29104
	ds_read_b128 v[166:169], v1 offset:33200
	s_waitcnt lgkmcnt(9)
	v_pk_fma_f32 v[226:227], v[98:99], v[42:43], v[226:227]
	v_pk_fma_f32 v[228:229], v[102:103], v[42:43], v[228:229]
	v_pk_fma_f32 v[230:231], v[106:107], v[42:43], v[230:231]
	v_pk_fma_f32 v[232:233], v[110:111], v[42:43], v[232:233]
	v_pk_fma_f32 v[234:235], v[114:115], v[42:43], v[234:235]
	v_pk_fma_f32 v[236:237], v[118:119], v[42:43], v[236:237]
	v_pk_fma_f32 v[238:239], v[122:123], v[42:43], v[238:239]
	v_pk_fma_f32 v[240:241], v[126:127], v[42:43], v[240:241]
	v_pk_fma_f32 v[242:243], v[130:131], v[42:43], v[242:243]
	v_pk_fma_f32 v[226:227], v[100:101], v[44:45], v[226:227]
	v_pk_fma_f32 v[228:229], v[104:105], v[44:45], v[228:229]
	v_pk_fma_f32 v[230:231], v[108:109], v[44:45], v[230:231]
	v_pk_fma_f32 v[232:233], v[112:113], v[44:45], v[232:233]
	v_pk_fma_f32 v[234:235], v[116:117], v[44:45], v[234:235]
	v_pk_fma_f32 v[236:237], v[120:121], v[44:45], v[236:237]
	v_pk_fma_f32 v[238:239], v[124:125], v[44:45], v[238:239]
	v_pk_fma_f32 v[240:241], v[128:129], v[44:45], v[240:241]
	v_pk_fma_f32 v[242:243], v[132:133], v[44:45], v[242:243]
	ds_read_b128 v[98:101], v1 offset:448
	ds_read_b128 v[102:105], v1 offset:4544
	ds_read_b128 v[106:109], v1 offset:8640
	ds_read_b128 v[110:113], v1 offset:12736
	ds_read_b128 v[114:117], v1 offset:16832
	ds_read_b128 v[118:121], v1 offset:20928
	ds_read_b128 v[122:125], v1 offset:25024
	ds_read_b128 v[126:129], v1 offset:29120
	ds_read_b128 v[130:133], v1 offset:33216
	s_waitcnt lgkmcnt(9)
	v_pk_fma_f32 v[226:227], v[134:135], v[46:47], v[226:227]
	v_pk_fma_f32 v[228:229], v[138:139], v[46:47], v[228:229]
	v_pk_fma_f32 v[230:231], v[142:143], v[46:47], v[230:231]
	v_pk_fma_f32 v[232:233], v[146:147], v[46:47], v[232:233]
	v_pk_fma_f32 v[234:235], v[150:151], v[46:47], v[234:235]
	v_pk_fma_f32 v[236:237], v[154:155], v[46:47], v[236:237]
	v_pk_fma_f32 v[238:239], v[158:159], v[46:47], v[238:239]
	v_pk_fma_f32 v[240:241], v[162:163], v[46:47], v[240:241]
	v_pk_fma_f32 v[242:243], v[166:167], v[46:47], v[242:243]
	v_pk_fma_f32 v[226:227], v[136:137], v[48:49], v[226:227]
	v_pk_fma_f32 v[228:229], v[140:141], v[48:49], v[228:229]
	v_pk_fma_f32 v[230:231], v[144:145], v[48:49], v[230:231]
	v_pk_fma_f32 v[232:233], v[148:149], v[48:49], v[232:233]
	v_pk_fma_f32 v[234:235], v[152:153], v[48:49], v[234:235]
	v_pk_fma_f32 v[236:237], v[156:157], v[48:49], v[236:237]
	v_pk_fma_f32 v[238:239], v[160:161], v[48:49], v[238:239]
	v_pk_fma_f32 v[240:241], v[164:165], v[48:49], v[240:241]
	v_pk_fma_f32 v[242:243], v[168:169], v[48:49], v[242:243]
	ds_read_b128 v[134:137], v1 offset:464
	ds_read_b128 v[138:141], v1 offset:4560
	ds_read_b128 v[142:145], v1 offset:8656
	ds_read_b128 v[146:149], v1 offset:12752
	ds_read_b128 v[150:153], v1 offset:16848
	ds_read_b128 v[154:157], v1 offset:20944
	ds_read_b128 v[158:161], v1 offset:25040
	ds_read_b128 v[162:165], v1 offset:29136
	ds_read_b128 v[166:169], v1 offset:33232
	s_waitcnt lgkmcnt(9)
; #define LAS __attribute__((address_space(3)))
; __device__ __forceinline__ void prologue(const __attribute__((address_space(4))) Args& a, ldsp lds, int gw, int NGW, int wave, int lane, const int tid, const int bid, const int G) {
;     ...
;         for (int k = wave * 128; k < wave * 128 + 128; k += 16) {
;             float wv[16];
; #pragma unroll
;             for (int q = 0; q < 16; ++q) wv[q] = Wl[(size_t)(k + q) * NMOD];
; #pragma unroll
;             for (int q4 = 0; q4 < 4; ++q4)
; #pragma unroll
;                 for (int j = 0; j < 9; ++j) { const f32x4 s4 = *(const LAS f32x4*)(sc + j * D + k + 4 * q4); acc[j] += s4[0] * wv[4 * q4] + s4[1] * wv[4 * q4 + 1] + s4[2] * wv[4 * q4 + 2] + s4[3] * wv[4 * q4 + 3]; }
;         }
; #pragma unroll
;         for (int j = 0; j < 9; ++j) red[(wave * 9 + j) * 64 + lane] = acc[j];
	v_pk_fma_f32 v[226:227], v[98:99], v[50:51], v[226:227]
	v_pk_fma_f32 v[228:229], v[102:103], v[50:51], v[228:229]
	v_pk_fma_f32 v[230:231], v[106:107], v[50:51], v[230:231]
	v_pk_fma_f32 v[232:233], v[110:111], v[50:51], v[232:233]
	v_pk_fma_f32 v[234:235], v[114:115], v[50:51], v[234:235]
	v_pk_fma_f32 v[236:237], v[118:119], v[50:51], v[236:237]
	v_pk_fma_f32 v[238:239], v[122:123], v[50:51], v[238:239]
	v_pk_fma_f32 v[240:241], v[126:127], v[50:51], v[240:241]
	v_pk_fma_f32 v[242:243], v[130:131], v[50:51], v[242:243]
	v_pk_fma_f32 v[226:227], v[100:101], v[52:53], v[226:227]
	v_pk_fma_f32 v[228:229], v[104:105], v[52:53], v[228:229]
	v_pk_fma_f32 v[230:231], v[108:109], v[52:53], v[230:231]
	v_pk_fma_f32 v[232:233], v[112:113], v[52:53], v[232:233]
	v_pk_fma_f32 v[234:235], v[116:117], v[52:53], v[234:235]
	v_pk_fma_f32 v[236:237], v[120:121], v[52:53], v[236:237]
	v_pk_fma_f32 v[238:239], v[124:125], v[52:53], v[238:239]
	v_pk_fma_f32 v[240:241], v[128:129], v[52:53], v[240:241]
	v_pk_fma_f32 v[242:243], v[132:133], v[52:53], v[242:243]
	ds_read_b128 v[98:101], v1 offset:480
	ds_read_b128 v[102:105], v1 offset:4576
	ds_read_b128 v[106:109], v1 offset:8672
	ds_read_b128 v[110:113], v1 offset:12768
	ds_read_b128 v[114:117], v1 offset:16864
	ds_read_b128 v[118:121], v1 offset:20960
	ds_read_b128 v[122:125], v1 offset:25056
	ds_read_b128 v[126:129], v1 offset:29152
	ds_read_b128 v[130:133], v1 offset:33248
	s_waitcnt lgkmcnt(9)
	v_pk_fma_f32 v[226:227], v[134:135], v[54:55], v[226:227]
	v_pk_fma_f32 v[228:229], v[138:139], v[54:55], v[228:229]
	v_pk_fma_f32 v[230:231], v[142:143], v[54:55], v[230:231]
	v_pk_fma_f32 v[232:233], v[146:147], v[54:55], v[232:233]
	v_pk_fma_f32 v[234:235], v[150:151], v[54:55], v[234:235]
	v_pk_fma_f32 v[236:237], v[154:155], v[54:55], v[236:237]
	v_pk_fma_f32 v[238:239], v[158:159], v[54:55], v[238:239]
	v_pk_fma_f32 v[240:241], v[162:163], v[54:55], v[240:241]
	v_pk_fma_f32 v[242:243], v[166:167], v[54:55], v[242:243]
	v_pk_fma_f32 v[226:227], v[136:137], v[56:57], v[226:227]
	v_pk_fma_f32 v[228:229], v[140:141], v[56:57], v[228:229]
	v_pk_fma_f32 v[230:231], v[144:145], v[56:57], v[230:231]
	v_pk_fma_f32 v[232:233], v[148:149], v[56:57], v[232:233]
	v_pk_fma_f32 v[234:235], v[152:153], v[56:57], v[234:235]
	v_pk_fma_f32 v[236:237], v[156:157], v[56:57], v[236:237]
	v_pk_fma_f32 v[238:239], v[160:161], v[56:57], v[238:239]
	v_pk_fma_f32 v[240:241], v[164:165], v[56:57], v[240:241]
	v_pk_fma_f32 v[242:243], v[168:169], v[56:57], v[242:243]
	ds_read_b128 v[134:137], v1 offset:496
	ds_read_b128 v[138:141], v1 offset:4592
	ds_read_b128 v[142:145], v1 offset:8688
	ds_read_b128 v[146:149], v1 offset:12784
	ds_read_b128 v[150:153], v1 offset:16880
	ds_read_b128 v[154:157], v1 offset:20976
	ds_read_b128 v[158:161], v1 offset:25072
	ds_read_b128 v[162:165], v1 offset:29168
	ds_read_b128 v[166:169], v1 offset:33264
	s_waitcnt lgkmcnt(9)
	v_pk_fma_f32 v[226:227], v[98:99], v[58:59], v[226:227]
	v_pk_fma_f32 v[228:229], v[102:103], v[58:59], v[228:229]
	v_pk_fma_f32 v[230:231], v[106:107], v[58:59], v[230:231]
	v_pk_fma_f32 v[232:233], v[110:111], v[58:59], v[232:233]
	v_pk_fma_f32 v[234:235], v[114:115], v[58:59], v[234:235]
	v_pk_fma_f32 v[236:237], v[118:119], v[58:59], v[236:237]
	v_pk_fma_f32 v[238:239], v[122:123], v[58:59], v[238:239]
	v_pk_fma_f32 v[240:241], v[126:127], v[58:59], v[240:241]
	v_pk_fma_f32 v[242:243], v[130:131], v[58:59], v[242:243]
	v_pk_fma_f32 v[226:227], v[100:101], v[60:61], v[226:227]
	v_pk_fma_f32 v[228:229], v[104:105], v[60:61], v[228:229]
	v_pk_fma_f32 v[230:231], v[108:109], v[60:61], v[230:231]
	v_pk_fma_f32 v[232:233], v[112:113], v[60:61], v[232:233]
	v_pk_fma_f32 v[234:235], v[116:117], v[60:61], v[234:235]
	v_pk_fma_f32 v[236:237], v[120:121], v[60:61], v[236:237]
	v_pk_fma_f32 v[238:239], v[124:125], v[60:61], v[238:239]
	v_pk_fma_f32 v[240:241], v[128:129], v[60:61], v[240:241]
	v_pk_fma_f32 v[242:243], v[132:133], v[60:61], v[242:243]
	s_waitcnt lgkmcnt(0)
	v_pk_fma_f32 v[226:227], v[134:135], v[62:63], v[226:227]
	v_pk_fma_f32 v[228:229], v[138:139], v[62:63], v[228:229]
	v_pk_fma_f32 v[230:231], v[142:143], v[62:63], v[230:231]
	v_pk_fma_f32 v[232:233], v[146:147], v[62:63], v[232:233]
	v_pk_fma_f32 v[234:235], v[150:151], v[62:63], v[234:235]
	v_pk_fma_f32 v[236:237], v[154:155], v[62:63], v[236:237]
	v_pk_fma_f32 v[238:239], v[158:159], v[62:63], v[238:239]
	v_pk_fma_f32 v[240:241], v[162:163], v[62:63], v[240:241]
	v_pk_fma_f32 v[242:243], v[166:167], v[62:63], v[242:243]
	v_pk_fma_f32 v[226:227], v[136:137], v[64:65], v[226:227]
	v_pk_fma_f32 v[228:229], v[140:141], v[64:65], v[228:229]
	v_pk_fma_f32 v[230:231], v[144:145], v[64:65], v[230:231]
	v_pk_fma_f32 v[232:233], v[148:149], v[64:65], v[232:233]
	v_pk_fma_f32 v[234:235], v[152:153], v[64:65], v[234:235]
	v_pk_fma_f32 v[236:237], v[156:157], v[64:65], v[236:237]
	v_pk_fma_f32 v[238:239], v[160:161], v[64:65], v[238:239]
	v_pk_fma_f32 v[240:241], v[164:165], v[64:65], v[240:241]
	v_pk_fma_f32 v[242:243], v[168:169], v[64:65], v[242:243]
	v_add_f32_e32 v78, v226, v227
	v_add_f32_e32 v79, v228, v229
	v_add_f32_e32 v84, v230, v231
	v_add_f32_e32 v85, v232, v233
	v_add_f32_e32 v82, v234, v235
	v_add_f32_e32 v83, v236, v237
	v_add_f32_e32 v80, v238, v239
	v_add_f32_e32 v81, v240, v241
	v_add_f32_e32 v92, v242, v243
	ds_write2st64_b32 v91, v78, v79 offset1:1
	ds_write2st64_b32 v91, v84, v85 offset0:2 offset1:3
	ds_write2st64_b32 v91, v82, v83 offset0:4 offset1:5
	ds_write2st64_b32 v91, v80, v81 offset0:6 offset1:7
	ds_write_b32 v91, v92 offset:2048
	s_waitcnt lgkmcnt(0)
	s_barrier
	s_and_saveexec_b64 s[8:9], s[4:5]
	s_cbranch_execz .LBB0_1276
	s_mul_i32 s13, s12, 0x1800
	s_add_i32 s14, s13, s6
	v_or_b32_e32 v0, s14, v87
	v_ashrrev_i32_e32 v1, 31, v0
	s_mul_hi_i32 s13, s12, 9
	s_mul_i32 s12, s12, 9
	v_lshl_add_u64 v[0:1], v[0:1], 2, s[10:11]
	v_lshl_add_u64 v[2:3], s[6:7], 2, v[72:73]
	s_mov_b64 s[6:7], 0
	v_mov_b32_e32 v4, v196
